# rwkv_prep: mix-coefficient rows staged in LDS (48 KB), per-output coefficient loads -> ds_read, waits -> lgkmcnt (no more store-ack in the load chain) - on top of v72
# baseline (speedup 1.0000x reference)
.LBB0_246:
	s_andn2_b64 vcc, exec, s[8:9]
	s_cbranch_vccnz .LBB0_329
	s_mov_b32 s0, s80
	s_mov_b32 s2, -1
	s_lshl_b32 s0, s0, 6
	v_mbcnt_lo_u32_b32 v0, s2, 0
	v_mbcnt_hi_u32_b32 v0, s2, v0
	v_readlane_b32 s2, v250, 6
	s_add_i32 s0, s0, s2
	s_mov_b64 s[18:19], s[96:97]
	v_add_u32_e32 v60, s0, v0
	s_mov_b32 s0, 0x400000
	s_mov_b64 s[8:9], s[96:97]
	s_mov_b64 s[12:13], s[96:97]
	v_cmp_gt_i32_e32 vcc, s0, v60
	s_and_saveexec_b64 s[16:17], vcc
	s_cbranch_execz .LBB0_273
	s_load_dwordx2 s[2:3], s[18:19], 0x110
	s_nop 0
	s_load_dwordx2 s[18:19], s[8:9], 0x58
	s_nop 0
	s_load_dwordx2 s[8:9], s[12:13], 0x110
	v_readlane_b32 s0, v253, 44
	v_mov_b32_e32 v0, 0
	s_waitcnt lgkmcnt(0)
	s_add_u32 s20, s2, s0
	s_addc_u32 s21, s3, 0
	s_add_u32 s22, s8, 0x22b00000
	v_lshlrev_b32_e32 v61, 3, v60
	s_addc_u32 s23, s9, 0
	s_mov_b64 s[26:27], 0
	v_mov_b32_e32 v1, v0
	v_mov_b32_e32 v2, v0
	v_mov_b32_e32 v3, v0
	v_mov_b32_e32 v16, v0
	v_mov_b32_e32 v17, v0
	v_mov_b32_e32 v18, v0
	v_mov_b32_e32 v19, v0
	v_mov_b32_e32 v20, v0
	v_mov_b32_e32 v21, v0
	v_mov_b32_e32 v22, v0
	v_mov_b32_e32 v23, v0
	v_mov_b32_e32 v4, v0
	v_mov_b32_e32 v5, v0
	v_mov_b32_e32 v6, v0
	v_mov_b32_e32 v7, v0
	v_mov_b32_e32 v8, v0
	v_mov_b32_e32 v9, v0
	v_mov_b32_e32 v10, v0
	v_mov_b32_e32 v11, v0
	v_mov_b32_e32 v12, v0
	v_mov_b32_e32 v13, v0
	v_mov_b32_e32 v14, v0
	v_mov_b32_e32 v15, v0
	s_barrier
	s_mov_b32 s98, -1
	v_mbcnt_lo_u32_b32 v124, s98, 0
	v_mbcnt_hi_u32_b32 v124, s98, v124
	s_lshl_b32 s98, s80, 6
	v_add_u32_e32 v124, s98, v124
	v_lshlrev_b32_e32 v124, 4, v124
	global_load_dwordx4 v[100:103], v124, s[18:19]
	v_add_u32_e32 v125, 0x2000, v124
	global_load_dwordx4 v[104:107], v125, s[18:19]
	v_add_u32_e32 v125, 0x4000, v124
	global_load_dwordx4 v[108:111], v125, s[18:19]
	v_add_u32_e32 v125, 0x6000, v124
	global_load_dwordx4 v[112:115], v125, s[18:19]
	v_add_u32_e32 v125, 0x8000, v124
	global_load_dwordx4 v[116:119], v125, s[18:19]
	v_add_u32_e32 v125, 0xa000, v124
	global_load_dwordx4 v[120:123], v125, s[18:19]
	s_waitcnt vmcnt(0)
	ds_write_b128 v124, v[100:103]
	ds_write_b128 v124, v[104:107] offset:8192
	ds_write_b128 v124, v[108:111] offset:16384
	ds_write_b128 v124, v[112:115] offset:24576
	ds_write_b128 v124, v[116:119] offset:32768
	ds_write_b128 v124, v[120:123] offset:40960
	s_waitcnt lgkmcnt(0)
	s_barrier
	s_branch .LBB0_250

.LBB0_264:
	s_or_b64 exec, exec, s[8:9]
	s_waitcnt vmcnt(0)
	v_cvt_f32_f16_sdwa v43, v24 dst_sel:DWORD dst_unused:UNUSED_PAD src0_sel:WORD_1
	v_cvt_f32_f16_e32 v42, v24
	v_cvt_f32_f16_sdwa v47, v25 dst_sel:DWORD dst_unused:UNUSED_PAD src0_sel:WORD_1
	v_cvt_f32_f16_e32 v46, v25
	v_cvt_f32_f16_sdwa v25, v29 dst_sel:DWORD dst_unused:UNUSED_PAD src0_sel:WORD_1
	v_cvt_f32_f16_e32 v24, v29
	v_cvt_f32_f16_sdwa v51, v27 dst_sel:DWORD dst_unused:UNUSED_PAD src0_sel:WORD_1
	v_cvt_f32_f16_e32 v50, v27
	v_cvt_f32_f16_sdwa v37, v28 dst_sel:DWORD dst_unused:UNUSED_PAD src0_sel:WORD_1
	v_pk_add_f32 v[52:53], v[24:25], v[46:47] neg_lo:[0,1] neg_hi:[0,1]
	v_cvt_f32_f16_sdwa v25, v31 dst_sel:DWORD dst_unused:UNUSED_PAD src0_sel:WORD_1
	v_cvt_f32_f16_e32 v24, v31
	v_cvt_f32_f16_e32 v36, v28
	v_lshl_add_u64 v[28:29], s[22:23], 0, v[34:35]
	v_cvt_f32_f16_sdwa v55, v30 dst_sel:DWORD dst_unused:UNUSED_PAD src0_sel:WORD_1
	v_pk_add_f32 v[56:57], v[24:25], v[50:51] neg_lo:[0,1] neg_hi:[0,1]
	v_lshlrev_b32_e32 v24, 2, v58
	v_cvt_f32_f16_e32 v54, v30
	v_pk_add_f32 v[48:49], v[36:37], v[42:43] neg_lo:[0,1] neg_hi:[0,1]
	v_lshl_add_u64 v[58:59], v[28:29], 0, v[224:225]
	ds_read_b128 v[28:31], v24 offset:16
	ds_read_b128 v[34:37], v24
	v_cvt_f32_f16_sdwa v45, v26 dst_sel:DWORD dst_unused:UNUSED_PAD src0_sel:WORD_1
	v_cvt_f32_f16_e32 v44, v26
	v_mov_b32_e32 v25, v225
	v_lshl_add_u64 v[26:27], s[18:19], 0, v[24:25]
	s_movk_i32 s0, 0x4000
	v_pk_add_f32 v[54:55], v[54:55], v[44:45] neg_lo:[0,1] neg_hi:[0,1]
	s_mov_b64 s[2:3], 0x4000
	s_waitcnt lgkmcnt(0)
	v_pk_fma_f32 v[24:25], v[36:37], v[52:53], v[46:47]
	v_pk_fma_f32 v[34:35], v[34:35], v[48:49], v[42:43]
	v_pk_fma_f32 v[36:37], v[30:31], v[56:57], v[50:51]
	v_pk_fma_f32 v[30:31], v[28:29], v[54:55], v[44:45]
	v_cvt_pk_bf16_f32 v28, v34, v35
	v_cvt_pk_bf16_f32 v29, v24, v25
	v_cvt_pk_bf16_f32 v30, v30, v31
	v_cvt_pk_bf16_f32 v31, v36, v37
	global_store_dwordx4 v[58:59], v[28:31], off
	v_lshl_add_u64 v[24:25], v[26:27], 0, s[2:3]
	s_mov_b64 s[2:3], 0x6000
	v_add_co_u32_e32 v28, vcc, s0, v26
	s_brev_b32 s0, 32
	s_nop 0
	v_addc_co_u32_e32 v29, vcc, 0, v27, vcc
	v_subrev_u32_e32 v126, s18, v28
	ds_read_b128 v[28:31], v126
	s_nop 0
	v_subrev_u32_e32 v126, s18, v24
	ds_read_b128 v[34:37], v126 offset:16
	s_waitcnt lgkmcnt(1)
	v_pk_fma_f32 v[30:31], v[30:31], v[52:53], v[46:47]
	v_pk_fma_f32 v[28:29], v[28:29], v[48:49], v[42:43]
	s_waitcnt lgkmcnt(0)
	v_pk_fma_f32 v[34:35], v[34:35], v[54:55], v[44:45]
	v_pk_fma_f32 v[36:37], v[36:37], v[56:57], v[50:51]
	v_cvt_pk_bf16_f32 v28, v28, v29
	v_cvt_pk_bf16_f32 v29, v30, v31
	v_cvt_pk_bf16_f32 v30, v34, v35
	v_add_co_u32_e32 v34, vcc, s0, v58
	v_cvt_pk_bf16_f32 v31, v36, v37
	s_nop 0
	v_addc_co_u32_e32 v35, vcc, 0, v59, vcc
	s_movk_i32 s0, 0x6000
	global_store_dwordx4 v[34:35], v[28:31], off
	s_nop 1
	v_add_co_u32_e32 v30, vcc, s0, v26
	v_lshl_add_u64 v[28:29], v[26:27], 0, s[2:3]
	s_nop 0
	v_addc_co_u32_e32 v31, vcc, 0, v27, vcc
	v_subrev_u32_e32 v126, s18, v30
	ds_read_b128 v[34:37], v126
	v_subrev_u32_e32 v126, s18, v28
	ds_read_b128 v[62:65], v126 offset:16
	s_brev_b32 s0, 16
	s_mov_b64 s[2:3], 0x2000
	s_waitcnt lgkmcnt(1)
	v_pk_fma_f32 v[30:31], v[52:53], v[36:37], v[46:47]
	v_pk_fma_f32 v[34:35], v[48:49], v[34:35], v[42:43]
	s_waitcnt lgkmcnt(0)
	v_pk_fma_f32 v[64:65], v[56:57], v[64:65], v[50:51]
	v_pk_fma_f32 v[36:37], v[54:55], v[62:63], v[44:45]
	v_cvt_pk_bf16_f32 v34, v34, v35
	v_cvt_pk_bf16_f32 v35, v30, v31
	v_add_co_u32_e32 v30, vcc, s0, v58
	v_cvt_pk_bf16_f32 v36, v36, v37
	v_cvt_pk_bf16_f32 v37, v64, v65
	v_addc_co_u32_e32 v31, vcc, 0, v59, vcc
	s_movk_i32 s0, 0x2000
	global_store_dwordx4 v[30:31], v[34:37], off
	v_lshl_add_u64 v[30:31], v[26:27], 0, s[2:3]
	s_mov_b64 s[2:3], 0x8000
	v_add_co_u32_e32 v34, vcc, s0, v26
	s_brev_b32 s0, 48
	s_nop 0
	v_addc_co_u32_e32 v35, vcc, 0, v27, vcc
	v_subrev_u32_e32 v126, s18, v34
	ds_read_b128 v[34:37], v126
	s_nop 0
	v_subrev_u32_e32 v126, s18, v30
	ds_read_b128 v[62:65], v126 offset:16
	s_waitcnt lgkmcnt(1)
	v_pk_fma_f32 v[36:37], v[52:53], v[36:37], v[46:47]
	v_pk_fma_f32 v[34:35], v[48:49], v[34:35], v[42:43]
	s_waitcnt lgkmcnt(0)
	v_pk_fma_f32 v[62:63], v[54:55], v[62:63], v[44:45]
	v_pk_fma_f32 v[64:65], v[56:57], v[64:65], v[50:51]
	v_cvt_pk_bf16_f32 v34, v34, v35
	v_cvt_pk_bf16_f32 v35, v36, v37
	v_cvt_pk_bf16_f32 v36, v62, v63
	v_add_co_u32_e32 v62, vcc, s0, v58
	v_cvt_pk_bf16_f32 v37, v64, v65
	s_nop 0
	v_addc_co_u32_e32 v63, vcc, 0, v59, vcc
	s_mov_b32 s0, 0x8000
	global_store_dwordx4 v[62:63], v[34:37], off
	s_nop 1
	v_add_co_u32_e32 v36, vcc, s0, v26
	v_lshl_add_u64 v[34:35], v[26:27], 0, s[2:3]
	s_nop 0
	v_addc_co_u32_e32 v37, vcc, 0, v27, vcc
	v_subrev_u32_e32 v126, s18, v36
	ds_read_b128 v[62:65], v126
	v_subrev_u32_e32 v126, s18, v34
	ds_read_b128 v[66:69], v126 offset:16
	s_brev_b32 s0, 8
	s_mov_b64 s[2:3], 0xa000
	s_waitcnt lgkmcnt(1)
	v_pk_fma_f32 v[36:37], v[52:53], v[64:65], v[46:47]
	v_pk_fma_f32 v[62:63], v[48:49], v[62:63], v[42:43]
	s_waitcnt lgkmcnt(0)
	v_pk_fma_f32 v[68:69], v[56:57], v[68:69], v[50:51]
	v_pk_fma_f32 v[64:65], v[54:55], v[66:67], v[44:45]
	v_cvt_pk_bf16_f32 v62, v62, v63
	v_cvt_pk_bf16_f32 v63, v36, v37
	v_add_co_u32_e32 v36, vcc, s0, v58
	v_cvt_pk_bf16_f32 v64, v64, v65
	v_cvt_pk_bf16_f32 v65, v68, v69
	v_addc_co_u32_e32 v37, vcc, 0, v59, vcc
	s_mov_b32 s0, 0xa000
	global_store_dwordx4 v[36:37], v[62:65], off
	v_lshl_add_u64 v[36:37], v[26:27], 0, s[2:3]
	s_nop 0
	v_add_co_u32_e32 v62, vcc, s0, v26
	s_nop 1
	v_addc_co_u32_e32 v63, vcc, 0, v27, vcc
	v_subrev_u32_e32 v126, s18, v62
	ds_read_b128 v[62:65], v126
	s_nop 0
	v_subrev_u32_e32 v126, s18, v36
	ds_read_b128 v[66:69], v126 offset:16
	s_waitcnt lgkmcnt(1)
	v_pk_fma_f32 v[46:47], v[52:53], v[64:65], v[46:47]
	v_pk_fma_f32 v[42:43], v[48:49], v[62:63], v[42:43]
	s_waitcnt lgkmcnt(0)
	v_pk_fma_f32 v[48:49], v[56:57], v[68:69], v[50:51]
	v_pk_fma_f32 v[44:45], v[54:55], v[66:67], v[44:45]
	v_cvt_pk_bf16_f32 v42, v42, v43
	v_cvt_pk_bf16_f32 v43, v46, v47
	v_add_co_u32_e32 v46, vcc, 0x14000000, v58
	v_cvt_pk_bf16_f32 v44, v44, v45
	v_cvt_pk_bf16_f32 v45, v48, v49
	v_addc_co_u32_e32 v47, vcc, 0, v59, vcc
	global_store_dwordx4 v[46:47], v[42:45], off
	s_and_saveexec_b64 s[34:35], s[42:43]
	s_cbranch_execz .LBB0_268
	v_subrev_u32_e32 v126, s18, v26
	ds_read_b128 v[62:65], v126 offset:16
	v_subrev_u32_e32 v126, s18, v26
	ds_read_b128 v[66:69], v126
	v_cvt_f32_f16_sdwa v47, v5 dst_sel:DWORD dst_unused:UNUSED_PAD src0_sel:WORD_1
	v_cvt_f32_f16_e32 v46, v5
	v_cvt_f32_f16_sdwa v51, v1 dst_sel:DWORD dst_unused:UNUSED_PAD src0_sel:WORD_1
	v_cvt_f32_f16_e32 v50, v1
	v_cvt_f32_f16_sdwa v43, v4 dst_sel:DWORD dst_unused:UNUSED_PAD src0_sel:WORD_1
	v_cvt_f32_f16_e32 v42, v4
	v_cvt_f32_f16_sdwa v49, v0 dst_sel:DWORD dst_unused:UNUSED_PAD src0_sel:WORD_1
	v_cvt_f32_f16_e32 v48, v0
	v_cvt_f32_f16_sdwa v45, v6 dst_sel:DWORD dst_unused:UNUSED_PAD src0_sel:WORD_1
	v_cvt_f32_f16_e32 v44, v6
	v_cvt_f32_f16_sdwa v55, v2 dst_sel:DWORD dst_unused:UNUSED_PAD src0_sel:WORD_1
	v_cvt_f32_f16_e32 v54, v2
	v_pk_add_f32 v[52:53], v[50:51], v[46:47] neg_lo:[0,1] neg_hi:[0,1]
	v_cvt_f32_f16_sdwa v51, v7 dst_sel:DWORD dst_unused:UNUSED_PAD src0_sel:WORD_1
	v_cvt_f32_f16_e32 v50, v7
	v_cvt_f32_f16_sdwa v57, v3 dst_sel:DWORD dst_unused:UNUSED_PAD src0_sel:WORD_1
	v_cvt_f32_f16_e32 v56, v3
	v_pk_add_f32 v[48:49], v[48:49], v[42:43] neg_lo:[0,1] neg_hi:[0,1]
	v_pk_add_f32 v[54:55], v[54:55], v[44:45] neg_lo:[0,1] neg_hi:[0,1]
	v_lshlrev_b64 v[40:41], 12, v[40:41]
	v_pk_add_f32 v[56:57], v[56:57], v[50:51] neg_lo:[0,1] neg_hi:[0,1]
	v_lshl_add_u64 v[40:41], s[22:23], 0, v[40:41]
	v_lshl_add_u64 v[40:41], v[40:41], 0, v[224:225]
	s_brev_b32 s0, 32
	s_waitcnt lgkmcnt(0)
	v_pk_fma_f32 v[58:59], v[52:53], v[68:69], v[46:47]
	v_pk_fma_f32 v[66:67], v[48:49], v[66:67], v[42:43]
	v_pk_fma_f32 v[68:69], v[56:57], v[64:65], v[50:51]
	v_pk_fma_f32 v[64:65], v[54:55], v[62:63], v[44:45]
	v_cvt_pk_bf16_f32 v62, v66, v67
	v_cvt_pk_bf16_f32 v63, v58, v59
	v_cvt_pk_bf16_f32 v64, v64, v65
	v_cvt_pk_bf16_f32 v65, v68, v69
	global_store_dwordx4 v[40:41], v[62:65], off
	v_subrev_u32_e32 v126, s18, v24
	ds_read_b128 v[62:65], v126 offset:16
	s_nop 0
	v_subrev_u32_e32 v126, s18, v24
	ds_read_b128 v[66:69], v126
	s_waitcnt lgkmcnt(0)
	v_pk_fma_f32 v[58:59], v[52:53], v[68:69], v[46:47]
	v_pk_fma_f32 v[66:67], v[48:49], v[66:67], v[42:43]
	v_pk_fma_f32 v[68:69], v[56:57], v[64:65], v[50:51]
	v_pk_fma_f32 v[64:65], v[54:55], v[62:63], v[44:45]
	v_cvt_pk_bf16_f32 v63, v58, v59
	v_add_co_u32_e32 v58, vcc, s0, v40
	v_cvt_pk_bf16_f32 v62, v66, v67
	v_cvt_pk_bf16_f32 v64, v64, v65
	v_cvt_pk_bf16_f32 v65, v68, v69
	v_addc_co_u32_e32 v59, vcc, 0, v41, vcc
	global_store_dwordx4 v[58:59], v[62:65], off
	v_subrev_u32_e32 v126, s18, v28
	ds_read_b128 v[62:65], v126 offset:16
	s_nop 0
	v_subrev_u32_e32 v126, s18, v28
	ds_read_b128 v[66:69], v126
	s_brev_b32 s0, 16
	s_waitcnt lgkmcnt(0)
	v_pk_fma_f32 v[58:59], v[52:53], v[68:69], v[46:47]
	v_pk_fma_f32 v[66:67], v[48:49], v[66:67], v[42:43]
	v_pk_fma_f32 v[68:69], v[56:57], v[64:65], v[50:51]
	v_pk_fma_f32 v[64:65], v[54:55], v[62:63], v[44:45]
	v_cvt_pk_bf16_f32 v63, v58, v59
	v_add_co_u32_e32 v58, vcc, s0, v40
	v_cvt_pk_bf16_f32 v62, v66, v67
	v_cvt_pk_bf16_f32 v64, v64, v65
	v_cvt_pk_bf16_f32 v65, v68, v69
	v_addc_co_u32_e32 v59, vcc, 0, v41, vcc
	global_store_dwordx4 v[58:59], v[62:65], off
	v_subrev_u32_e32 v126, s18, v30
	ds_read_b128 v[62:65], v126 offset:16
	s_nop 0
	v_subrev_u32_e32 v126, s18, v30
	ds_read_b128 v[66:69], v126
	s_brev_b32 s0, 48
	s_waitcnt lgkmcnt(0)
	v_pk_fma_f32 v[58:59], v[52:53], v[68:69], v[46:47]
	v_pk_fma_f32 v[66:67], v[48:49], v[66:67], v[42:43]
	v_pk_fma_f32 v[68:69], v[56:57], v[64:65], v[50:51]
	v_pk_fma_f32 v[64:65], v[54:55], v[62:63], v[44:45]
	v_cvt_pk_bf16_f32 v63, v58, v59
	v_add_co_u32_e32 v58, vcc, s0, v40
	v_cvt_pk_bf16_f32 v62, v66, v67
	v_cvt_pk_bf16_f32 v64, v64, v65
	v_cvt_pk_bf16_f32 v65, v68, v69
	v_addc_co_u32_e32 v59, vcc, 0, v41, vcc
	global_store_dwordx4 v[58:59], v[62:65], off
	v_subrev_u32_e32 v126, s18, v34
	ds_read_b128 v[62:65], v126 offset:16
	s_nop 0
	v_subrev_u32_e32 v126, s18, v34
	ds_read_b128 v[66:69], v126
	s_brev_b32 s0, 8
	s_waitcnt lgkmcnt(0)
	v_pk_fma_f32 v[58:59], v[52:53], v[68:69], v[46:47]
	v_pk_fma_f32 v[66:67], v[48:49], v[66:67], v[42:43]
	v_pk_fma_f32 v[68:69], v[56:57], v[64:65], v[50:51]
	v_pk_fma_f32 v[64:65], v[54:55], v[62:63], v[44:45]
	v_cvt_pk_bf16_f32 v63, v58, v59
	v_add_co_u32_e32 v58, vcc, s0, v40
	v_cvt_pk_bf16_f32 v62, v66, v67
	v_cvt_pk_bf16_f32 v64, v64, v65
	v_cvt_pk_bf16_f32 v65, v68, v69
	v_addc_co_u32_e32 v59, vcc, 0, v41, vcc
	global_store_dwordx4 v[58:59], v[62:65], off
	v_subrev_u32_e32 v126, s18, v36
	ds_read_b128 v[62:65], v126 offset:16
	s_nop 0
	v_subrev_u32_e32 v126, s18, v36
	ds_read_b128 v[66:69], v126
	v_add_co_u32_e32 v40, vcc, 0x14000000, v40
	s_waitcnt lgkmcnt(1)
	v_pk_fma_f32 v[44:45], v[54:55], v[62:63], v[44:45]
	s_waitcnt lgkmcnt(0)
	v_pk_fma_f32 v[46:47], v[52:53], v[68:69], v[46:47]
	v_pk_fma_f32 v[42:43], v[48:49], v[66:67], v[42:43]
	v_pk_fma_f32 v[48:49], v[56:57], v[64:65], v[50:51]
	v_cvt_pk_bf16_f32 v42, v42, v43
	v_cvt_pk_bf16_f32 v43, v46, v47
	v_cvt_pk_bf16_f32 v44, v44, v45
	v_cvt_pk_bf16_f32 v45, v48, v49
	v_addc_co_u32_e32 v41, vcc, 0, v41, vcc
	global_store_dwordx4 v[40:41], v[42:45], off
	s_or_b64 exec, exec, s[34:35]
	s_and_saveexec_b64 s[34:35], s[40:41]
	s_cbranch_execnz .LBB0_269

.LBB0_269:
	v_subrev_u32_e32 v126, s18, v26
	ds_read_b128 v[56:59], v126 offset:16
	v_subrev_u32_e32 v126, s18, v26
	ds_read_b128 v[62:65], v126
	v_cvt_f32_f16_sdwa v45, v9 dst_sel:DWORD dst_unused:UNUSED_PAD src0_sel:WORD_1
	v_cvt_f32_f16_e32 v44, v9
	v_cvt_f32_f16_sdwa v49, v17 dst_sel:DWORD dst_unused:UNUSED_PAD src0_sel:WORD_1
	v_cvt_f32_f16_e32 v48, v17
	v_cvt_f32_f16_sdwa v41, v8 dst_sel:DWORD dst_unused:UNUSED_PAD src0_sel:WORD_1
	v_cvt_f32_f16_e32 v40, v8
	v_cvt_f32_f16_sdwa v47, v16 dst_sel:DWORD dst_unused:UNUSED_PAD src0_sel:WORD_1
	v_cvt_f32_f16_e32 v46, v16
	v_cvt_f32_f16_sdwa v43, v10 dst_sel:DWORD dst_unused:UNUSED_PAD src0_sel:WORD_1
	v_cvt_f32_f16_e32 v42, v10
	v_cvt_f32_f16_sdwa v53, v18 dst_sel:DWORD dst_unused:UNUSED_PAD src0_sel:WORD_1
	v_cvt_f32_f16_e32 v52, v18
	v_pk_add_f32 v[50:51], v[48:49], v[44:45] neg_lo:[0,1] neg_hi:[0,1]
	v_cvt_f32_f16_sdwa v49, v11 dst_sel:DWORD dst_unused:UNUSED_PAD src0_sel:WORD_1
	v_cvt_f32_f16_e32 v48, v11
	v_cvt_f32_f16_sdwa v55, v19 dst_sel:DWORD dst_unused:UNUSED_PAD src0_sel:WORD_1
	v_cvt_f32_f16_e32 v54, v19
	v_pk_add_f32 v[46:47], v[46:47], v[40:41] neg_lo:[0,1] neg_hi:[0,1]
	v_pk_add_f32 v[52:53], v[52:53], v[42:43] neg_lo:[0,1] neg_hi:[0,1]
	v_lshlrev_b64 v[38:39], 12, v[38:39]
	v_pk_add_f32 v[54:55], v[54:55], v[48:49] neg_lo:[0,1] neg_hi:[0,1]
	v_lshl_add_u64 v[38:39], s[22:23], 0, v[38:39]
	v_lshl_add_u64 v[38:39], v[38:39], 0, v[224:225]
	s_brev_b32 s0, 32
	s_waitcnt lgkmcnt(1)
	v_pk_fma_f32 v[66:67], v[54:55], v[58:59], v[48:49]
	s_waitcnt lgkmcnt(0)
	v_pk_fma_f32 v[64:65], v[50:51], v[64:65], v[44:45]
	v_pk_fma_f32 v[62:63], v[46:47], v[62:63], v[40:41]
	v_pk_fma_f32 v[58:59], v[52:53], v[56:57], v[42:43]
	v_cvt_pk_bf16_f32 v56, v62, v63
	v_cvt_pk_bf16_f32 v57, v64, v65
	v_cvt_pk_bf16_f32 v58, v58, v59
	v_cvt_pk_bf16_f32 v59, v66, v67
	global_store_dwordx4 v[38:39], v[56:59], off
	v_subrev_u32_e32 v126, s18, v24
	ds_read_b128 v[56:59], v126 offset:16
	s_nop 0
	v_subrev_u32_e32 v126, s18, v24
	ds_read_b128 v[62:65], v126
	s_waitcnt lgkmcnt(1)
	v_pk_fma_f32 v[66:67], v[54:55], v[58:59], v[48:49]
	s_waitcnt lgkmcnt(0)
	v_pk_fma_f32 v[62:63], v[46:47], v[62:63], v[40:41]
	v_pk_fma_f32 v[64:65], v[50:51], v[64:65], v[44:45]
	v_pk_fma_f32 v[58:59], v[52:53], v[56:57], v[42:43]
	v_cvt_pk_bf16_f32 v56, v62, v63
	v_add_co_u32_e32 v62, vcc, s0, v38
	v_cvt_pk_bf16_f32 v57, v64, v65
	v_cvt_pk_bf16_f32 v58, v58, v59
	v_cvt_pk_bf16_f32 v59, v66, v67
	v_addc_co_u32_e32 v63, vcc, 0, v39, vcc
	global_store_dwordx4 v[62:63], v[56:59], off
	v_subrev_u32_e32 v126, s18, v28
	ds_read_b128 v[56:59], v126 offset:16
	s_nop 0
	v_subrev_u32_e32 v126, s18, v28
	ds_read_b128 v[62:65], v126
	s_brev_b32 s0, 16
	s_waitcnt lgkmcnt(1)
	v_pk_fma_f32 v[66:67], v[54:55], v[58:59], v[48:49]
	s_waitcnt lgkmcnt(0)
	v_pk_fma_f32 v[62:63], v[46:47], v[62:63], v[40:41]
	v_pk_fma_f32 v[64:65], v[50:51], v[64:65], v[44:45]
	v_pk_fma_f32 v[58:59], v[52:53], v[56:57], v[42:43]
	v_cvt_pk_bf16_f32 v56, v62, v63
	v_add_co_u32_e32 v62, vcc, s0, v38
	v_cvt_pk_bf16_f32 v57, v64, v65
	v_cvt_pk_bf16_f32 v58, v58, v59
	v_cvt_pk_bf16_f32 v59, v66, v67
	v_addc_co_u32_e32 v63, vcc, 0, v39, vcc
	global_store_dwordx4 v[62:63], v[56:59], off
	v_subrev_u32_e32 v126, s18, v30
	ds_read_b128 v[56:59], v126 offset:16
	s_nop 0
	v_subrev_u32_e32 v126, s18, v30
	ds_read_b128 v[62:65], v126
	s_brev_b32 s0, 48
	s_waitcnt lgkmcnt(1)
	v_pk_fma_f32 v[66:67], v[54:55], v[58:59], v[48:49]
	s_waitcnt lgkmcnt(0)
	v_pk_fma_f32 v[62:63], v[46:47], v[62:63], v[40:41]
	v_pk_fma_f32 v[64:65], v[50:51], v[64:65], v[44:45]
	v_pk_fma_f32 v[58:59], v[52:53], v[56:57], v[42:43]
	v_cvt_pk_bf16_f32 v56, v62, v63
	v_add_co_u32_e32 v62, vcc, s0, v38
	v_cvt_pk_bf16_f32 v57, v64, v65
	v_cvt_pk_bf16_f32 v58, v58, v59
	v_cvt_pk_bf16_f32 v59, v66, v67
	v_addc_co_u32_e32 v63, vcc, 0, v39, vcc
	global_store_dwordx4 v[62:63], v[56:59], off
	v_subrev_u32_e32 v126, s18, v34
	ds_read_b128 v[56:59], v126 offset:16
	s_nop 0
	v_subrev_u32_e32 v126, s18, v34
	ds_read_b128 v[62:65], v126
	s_brev_b32 s0, 8
	s_waitcnt lgkmcnt(1)
	v_pk_fma_f32 v[66:67], v[54:55], v[58:59], v[48:49]
	s_waitcnt lgkmcnt(0)
	v_pk_fma_f32 v[62:63], v[46:47], v[62:63], v[40:41]
	v_pk_fma_f32 v[64:65], v[50:51], v[64:65], v[44:45]
	v_pk_fma_f32 v[58:59], v[52:53], v[56:57], v[42:43]
	v_cvt_pk_bf16_f32 v56, v62, v63
	v_add_co_u32_e32 v62, vcc, s0, v38
	v_cvt_pk_bf16_f32 v57, v64, v65
	v_cvt_pk_bf16_f32 v58, v58, v59
	v_cvt_pk_bf16_f32 v59, v66, v67
	v_addc_co_u32_e32 v63, vcc, 0, v39, vcc
	global_store_dwordx4 v[62:63], v[56:59], off
	v_subrev_u32_e32 v126, s18, v36
	ds_read_b128 v[56:59], v126 offset:16
	s_nop 0
	v_subrev_u32_e32 v126, s18, v36
	ds_read_b128 v[62:65], v126
	v_add_co_u32_e32 v38, vcc, 0x14000000, v38
	s_waitcnt lgkmcnt(1)
	v_pk_fma_f32 v[42:43], v[52:53], v[56:57], v[42:43]
	s_waitcnt lgkmcnt(0)
	v_pk_fma_f32 v[44:45], v[50:51], v[64:65], v[44:45]
	v_pk_fma_f32 v[40:41], v[46:47], v[62:63], v[40:41]
	v_pk_fma_f32 v[46:47], v[54:55], v[58:59], v[48:49]
	v_cvt_pk_bf16_f32 v40, v40, v41
	v_cvt_pk_bf16_f32 v41, v44, v45
	v_cvt_pk_bf16_f32 v42, v42, v43
	v_cvt_pk_bf16_f32 v43, v46, v47
	v_addc_co_u32_e32 v39, vcc, 0, v39, vcc
	global_store_dwordx4 v[38:39], v[40:43], off
	s_or_b64 exec, exec, s[34:35]
	s_and_saveexec_b64 s[2:3], s[38:39]
	s_xor_b64 s[8:9], exec, s[2:3]
	s_cbranch_execnz .LBB0_267
